# HGRN2 mixer: next-chunk loads spread over the step (f at loop top, q after the token chain, v at the end)
# baseline (speedup 1.0000x reference)
; #define LAS __attribute__((address_space(3)))
; __device__ __forceinline__ unsigned cvt_pk_bf16(float lo, float hi) { unsigned r; asm("v_cvt_pk_bf16_f32 %0, %1, %2" : "=v"(r) : "v"(lo), "v"(hi)); return r; }
; __device__ __forceinline__ float bf_lo(unsigned u) { return __uint_as_float(u << 16); }
; template <int DK, bool IS_A, int NDV>
; __device__ __forceinline__ void mix_stream(const Params& p, LAS unsigned char* lds, int l, int rs, int T, int h, int dir, int dvh) {
;     ...
;     for (int n = 0; n < N; ++n) { constexpr int par = 0;
;         if (IS_A) {
;             float run0 = 0.f, run1 = 0.f;
; #pragma unroll
;             for (int i = 0; i < 8; ++i) { run0 += bf_lo(rf[par][i]); run1 += bf_hi(rf[par][i]); }
;             *(LAS f32x2*)(seg + sg * DK + 2 * cp) = (f32x2){run0, run1};
;         }
;         LDS_BARRIER();
;         if (n > 0) MIX_FLUSH(n - 1);
;         {
;             unsigned kt0[4], kt1[4], vt0[4], vt1[4];
;             if (IS_A) {
;                 float pre0 = 0.f, pre1 = 0.f, ref0 = 0.f, ref1 = 0.f, tot0 = 0.f, tot1 = 0.f;
; #pragma unroll
;                 for (int s8 = 0; s8 < 8; ++s8) { const f32x2 v = *(const LAS f32x2*)(seg + s8 * DK + 2 * cp);
;                     if (s8 < sg) { pre0 += v.x; pre1 += v.y; } if (s8 < 4) { ref0 += v.x; ref1 += v.y; } tot0 += v.x; tot1 += v.y; }
;                 f32x2 E = (f32x2){exp2_(fminf(fmaxf(pre0 - ref0, -115.f), 115.f)), exp2_(fminf(fmaxf(pre1 - ref1, -115.f), 115.f))};
; #pragma unroll
;                 for (int ip = 0; ip < 4; ++ip) { unsigned kp[2];
; #pragma unroll
;                     for (int e = 0; e < 2; ++e) { const int i = 2 * ip + e;
;                         const f32x2 f = (f32x2){exp2_(bf_lo(rf[par][i])), exp2_(bf_hi(rf[par][i]))};
;                         E = __builtin_elementwise_max(E * f, (f32x2){1e-35f, 1e-35f});
;                         const f32x2 r = (f32x2){rcp_(E.x), rcp_(E.y)};
;                         const f32x2 k = r - f * r;
;                         const f32x2 qv = (f32x2){bf_lo(rq[par][i]), bf_hi(rq[par][i])} * E;
;                         const int t = sg * 8 + i;
;                         const int cb4 = (4 * cp) ^ ((i >= 4 ? 16 : 0) ^ sgx);
;                         *(LAS unsigned*)(Qs + t * QP + cb4) = cvt_pk_bf16(qv.x, qv.y);
;                         kp[e] = cvt_pk_bf16(k.x, k.y);
;                         *(LAS unsigned*)(Ks + t * QP + cb4) = kp[e]; }
.LBB0_173:
	s_waitcnt vmcnt(0)
	v_lshlrev_b32_e32 v104, 16, v119
	v_and_b32_e32 v105, 0xffff0000, v119
	v_lshlrev_b32_e32 v102, 16, v125
	v_and_b32_e32 v103, 0xffff0000, v125
	v_pk_add_f32 v[0:1], v[104:105], 0 op_sel_hi:[1,0]
	v_lshlrev_b32_e32 v100, 16, v147
	v_and_b32_e32 v101, 0xffff0000, v147
	v_pk_add_f32 v[0:1], v[0:1], v[102:103]
	v_lshlrev_b32_e32 v98, 16, v151
	v_and_b32_e32 v99, 0xffff0000, v151
	v_pk_add_f32 v[0:1], v[0:1], v[100:101]
	v_lshlrev_b32_e32 v96, 16, v154
	v_and_b32_e32 v97, 0xffff0000, v154
	v_pk_add_f32 v[0:1], v[0:1], v[98:99]
	v_lshlrev_b32_e32 v94, 16, v158
	v_and_b32_e32 v95, 0xffff0000, v158
	v_pk_add_f32 v[0:1], v[0:1], v[96:97]
	s_waitcnt vmcnt(3)
	v_lshlrev_b32_e32 v92, 16, v161
	v_and_b32_e32 v93, 0xffff0000, v161
	v_pk_add_f32 v[0:1], v[0:1], v[94:95]
	v_lshlrev_b32_e32 v90, 16, v164
	v_and_b32_e32 v91, 0xffff0000, v164
	s_add_i32 s12, s17, 1
	s_cmp_ge_u32 s12, s78
	s_cbranch_scc1 .Lskip_f
	s_add_i32 s77, s11, 0x80
	s_add_i32 s13, s19, 0xffffff80
	s_and_b64 s[100:101], s[40:41], exec
	s_cselect_b32 s12, s77, s13
	s_add_i32 s12, s12, s18
	s_mul_hi_i32 s13, s12, 0x5000
	s_mulk_i32 s12, 0x5000
	s_add_u32 s100, s98, s12
	s_addc_u32 s101, s99, s13
	global_load_dword v119, v8, s[100:101]
	global_load_dword v125, v14, s[100:101]
	global_load_dword v147, v20, s[100:101]
	global_load_dword v151, v26, s[100:101]
	global_load_dword v154, v32, s[100:101]
	global_load_dword v158, v38, s[100:101]
	global_load_dword v161, v44, s[100:101]
	global_load_dword v164, v52, s[100:101]
.Lskip_f:
	v_pk_add_f32 v[0:1], v[0:1], v[92:93]
	v_add_u32_e32 v2, s36, v108
	v_pk_add_f32 v[0:1], v[0:1], v[90:91]
	ds_write_b64 v2, v[0:1]
	s_waitcnt lgkmcnt(0)
	s_barrier
	s_cmp_eq_u32 s17, 0
	s_cbranch_scc1 .LBB0_175
	ds_read_b128 v[0:3], v132
	ds_read_b128 v[4:7], v132 offset:16
	s_and_b64 s[12:13], s[40:41], exec
	s_cselect_b32 s12, s11, s19
	s_add_i32 s12, s12, s18
	v_mad_i64_i32 v[166:167], s[12:13], s12, v239, v[88:89]
	s_waitcnt lgkmcnt(0)
	global_store_dwordx4 v[166:167], v[0:3], off
	s_waitcnt lgkmcnt(0)
	global_store_dwordx4 v[166:167], v[4:7], off offset:16
.LBB0_175:
	ds_read2st64_b64 v[0:3], v108 offset1:1
	v_exp_f32_e32 v104, v104
	v_exp_f32_e32 v105, v105
	v_exp_f32_e32 v102, v102
	v_exp_f32_e32 v103, v103
	s_waitcnt lgkmcnt(0)
	v_add_f32_e32 v0, 0, v0
	v_add_f32_e32 v1, 0, v1
	v_cndmask_b32_e64 v4, 0, v1, s[58:59]
	v_cndmask_b32_e64 v5, 0, v0, s[58:59]
	v_add_f32_e32 v6, v2, v5
	v_add_f32_e32 v7, v3, v4
	v_cndmask_b32_e64 v4, v4, v7, s[60:61]
	v_cndmask_b32_e64 v5, v5, v6, s[60:61]
	v_add_f32_e32 v6, v0, v2
	v_add_f32_e32 v7, v1, v3
	ds_read2st64_b64 v[0:3], v108 offset0:2 offset1:3
	v_exp_f32_e32 v100, v100
	v_exp_f32_e32 v101, v101
	v_exp_f32_e32 v98, v98
	v_exp_f32_e32 v99, v99
	s_waitcnt lgkmcnt(0)
	v_add_f32_e32 v166, v0, v5
	v_add_f32_e32 v167, v1, v4
	v_cndmask_b32_e64 v4, v4, v167, s[62:63]
	v_cndmask_b32_e64 v5, v5, v166, s[62:63]
	v_add_f32_e32 v0, v6, v0
	v_add_f32_e32 v1, v7, v1
	v_add_f32_e32 v6, v2, v5
	v_add_f32_e32 v7, v3, v4
	v_add_f32_e32 v167, v0, v2
	v_add_f32_e32 v166, v1, v3
	ds_read2st64_b64 v[0:3], v108 offset0:4 offset1:5
	v_cndmask_b32_e64 v4, v4, v7, s[64:65]
	v_cndmask_b32_e64 v5, v5, v6, s[64:65]
	v_exp_f32_e32 v96, v96
	v_exp_f32_e32 v97, v97
	s_waitcnt lgkmcnt(0)
	v_add_f32_e32 v6, v0, v5
	v_add_f32_e32 v7, v1, v4
	v_cndmask_b32_e64 v4, v4, v7, s[66:67]
	v_cndmask_b32_e64 v5, v5, v6, s[66:67]
	v_add_f32_e32 v6, v2, v5
	v_add_f32_e32 v7, v3, v4
	v_cndmask_b32_e64 v168, v4, v7, s[68:69]
	v_cndmask_b32_e64 v169, v5, v6, s[68:69]
	ds_read2st64_b64 v[4:7], v108 offset0:6 offset1:7
	v_add_u32_e32 v172, s9, v112
	v_exp_f32_e32 v94, v94
	v_exp_f32_e32 v95, v95
	v_exp_f32_e32 v92, v92
	s_waitcnt lgkmcnt(0)
	v_add_f32_e32 v170, v4, v169
	v_add_f32_e32 v171, v5, v168
	v_cndmask_b32_e64 v168, v168, v171, s[70:71]
	v_cndmask_b32_e64 v169, v169, v170, s[70:71]
	v_add_f32_e32 v170, v6, v169
	v_add_f32_e32 v171, v7, v168
	v_cndmask_b32_e64 v171, v168, v171, s[72:73]
	v_cndmask_b32_e64 v168, v169, v170, s[72:73]
	v_sub_f32_e32 v168, v168, v167
	v_sub_f32_e32 v169, v171, v166
	v_med3_f32 v168, v168, s2, v240
	v_med3_f32 v169, v169, s2, v240
	v_exp_f32_e32 v168, v168
	v_exp_f32_e32 v169, v169
	v_exp_f32_e32 v93, v93
	v_exp_f32_e32 v90, v90
	v_exp_f32_e32 v91, v91
	v_pk_mul_f32 v[168:169], v[104:105], v[168:169]
	s_andn2_b64 vcc, exec, s[0:1]
	v_max_f32_e32 v169, 0x554ad2e, v169
	v_max_f32_e32 v168, 0x554ad2e, v168
	v_rcp_f32_e32 v170, v168
	v_rcp_f32_e32 v171, v169
	s_nop 0
	v_pk_fma_f32 v[104:105], v[104:105], v[170:171], v[170:171] neg_lo:[1,0,0] neg_hi:[1,0,0]
	v_lshlrev_b32_e32 v170, 16, v122
	v_and_b32_e32 v171, 0xffff0000, v122
	v_pk_mul_f32 v[170:171], v[168:169], v[170:171]
	v_pk_mul_f32 v[168:169], v[102:103], v[168:169]
	v_cvt_pk_bf16_f32 v170, v170, v171
	v_add_u32_e32 v171, s8, v112
	v_max_f32_e32 v169, 0x554ad2e, v169
	v_max_f32_e32 v168, 0x554ad2e, v168
	v_cvt_pk_bf16_f32 v104, v104, v105
	ds_write2st64_b32 v171, v170, v104 offset1:68
	v_rcp_f32_e32 v170, v168
	v_rcp_f32_e32 v171, v169
	s_nop 0
	v_pk_fma_f32 v[102:103], v[102:103], v[170:171], v[170:171] neg_lo:[1,0,0] neg_hi:[1,0,0]
	v_lshlrev_b32_e32 v170, 16, v124
	v_and_b32_e32 v171, 0xffff0000, v124
	v_pk_mul_f32 v[170:171], v[168:169], v[170:171]
	v_pk_mul_f32 v[168:169], v[100:101], v[168:169]
	v_cvt_pk_bf16_f32 v105, v170, v171
	v_cvt_pk_bf16_f32 v102, v102, v103
	s_nop 0
	v_max_f32_e32 v169, 0x554ad2e, v169
	v_max_f32_e32 v168, 0x554ad2e, v168
	v_rcp_f32_e32 v170, v168
	v_rcp_f32_e32 v171, v169
	s_nop 0
	v_pk_fma_f32 v[100:101], v[100:101], v[170:171], v[170:171] neg_lo:[1,0,0] neg_hi:[1,0,0]
; #define LAS __attribute__((address_space(3)))
; template <int DK, bool IS_A, int NDV>
; __device__ __forceinline__ void mix_stream(const Params& p, LAS unsigned char* lds, int l, int rs, int T, int h, int dir, int dvh) {
;     ...
;                 for (int ip = 0; ip < 4; ++ip) { unsigned kp[2];
; #pragma unroll
;                     for (int e = 0; e < 2; ++e) { const int i = 2 * ip + e;
;                         const f32x2 f = (f32x2){exp2_(bf_lo(rf[par][i])), exp2_(bf_hi(rf[par][i]))};
;                         E = __builtin_elementwise_max(E * f, (f32x2){1e-35f, 1e-35f});
;                         const f32x2 r = (f32x2){rcp_(E.x), rcp_(E.y)};
;                         const f32x2 k = r - f * r;
;                         const f32x2 qv = (f32x2){bf_lo(rq[par][i]), bf_hi(rq[par][i])} * E;
;                         const int t = sg * 8 + i;
;                         const int cb4 = (4 * cp) ^ ((i >= 4 ? 16 : 0) ^ sgx);
;                         *(LAS unsigned*)(Qs + t * QP + cb4) = cvt_pk_bf16(qv.x, qv.y);
;                         kp[e] = cvt_pk_bf16(k.x, k.y);
;                         *(LAS unsigned*)(Ks + t * QP + cb4) = kp[e]; }
;                     kt0[ip] = __builtin_amdgcn_perm(kp[1], kp[0], 0x05040100u); kt1[ip] = __builtin_amdgcn_perm(kp[1], kp[0], 0x07060302u);
;                     vt0[ip] = __builtin_amdgcn_perm(rv[par][2 * ip + 1], rv[par][2 * ip], 0x05040100u); vt1[ip] = __builtin_amdgcn_perm(rv[par][2 * ip + 1], rv[par][2 * ip], 0x07060302u);
;                 }
;                 if (sg == 0) { *(LAS f32x2*)(cdec + 2 * cp) = (f32x2){exp2_(fmaxf(tot0, -115.f)), exp2_(fmaxf(tot1, -115.f))};
;                                *(LAS f32x2*)(csc + 2 * cp) = (f32x2){exp2_(fmaxf(tot0 - ref0, -115.f)), exp2_(fmaxf(tot1 - ref1, -115.f))}; }
;                 *(LAS u32x4*)(Kt + (2 * cp) * TP + ((sg * 16) ^ (gk << 4))) = (u32x4){kt0[0], kt0[1], kt0[2], kt0[3]};
;                 *(LAS u32x4*)(Kt + (2 * cp + 1) * TP + ((sg * 16) ^ (gk << 4))) = (u32x4){kt1[0], kt1[1], kt1[2], kt1[3]};
;     ...
;             if (NDV == 8 || cp < 32) {
;             *(LAS u32x4*)(Vt + (2 * cp) * TP + ((sg * 16) ^ (gk << 4))) = (u32x4){vt0[0], vt0[1], vt0[2], vt0[3]};
;             *(LAS u32x4*)(Vt + (2 * cp + 1) * TP + ((sg * 16) ^ (gk << 4))) = (u32x4){vt1[0], vt1[1], vt1[2], vt1[3]}; }
;         }
; #pragma unroll
;         for (int dki = 0; dki < 2; ++dki) { f32x4 er;
	v_lshlrev_b32_e32 v170, 16, v129
	v_and_b32_e32 v171, 0xffff0000, v129
	v_pk_mul_f32 v[170:171], v[168:169], v[170:171]
	v_pk_mul_f32 v[168:169], v[98:99], v[168:169]
	v_cvt_pk_bf16_f32 v103, v170, v171
	v_cvt_pk_bf16_f32 v100, v100, v101
	v_add_u32_e32 v101, 0x4400, v172
	v_max_f32_e32 v169, 0x554ad2e, v169
	v_max_f32_e32 v168, 0x554ad2e, v168
	v_rcp_f32_e32 v170, v168
	v_rcp_f32_e32 v171, v169
	ds_write2_b32 v101, v102, v100 offset1:68
	ds_write2_b32 v172, v105, v103 offset1:68
	v_pk_fma_f32 v[98:99], v[98:99], v[170:171], v[170:171] neg_lo:[1,0,0] neg_hi:[1,0,0]
	v_lshlrev_b32_e32 v170, 16, v150
	v_and_b32_e32 v171, 0xffff0000, v150
	v_pk_mul_f32 v[170:171], v[168:169], v[170:171]
	v_pk_mul_f32 v[168:169], v[96:97], v[168:169]
	v_cvt_pk_bf16_f32 v101, v170, v171
	v_cvt_pk_bf16_f32 v98, v98, v99
	ds_write_b32 v172, v101 offset:544
	v_max_f32_e32 v169, 0x554ad2e, v169
	v_max_f32_e32 v168, 0x554ad2e, v168
	v_rcp_f32_e32 v170, v168
	v_rcp_f32_e32 v171, v169
	v_add_u32_e32 v101, 0x200, v133
	ds_write_b32 v172, v98 offset:17952
	v_pk_fma_f32 v[96:97], v[96:97], v[170:171], v[170:171] neg_lo:[1,0,0] neg_hi:[1,0,0]
	v_lshlrev_b32_e32 v170, 16, v153
	v_and_b32_e32 v171, 0xffff0000, v153
	v_pk_mul_f32 v[170:171], v[168:169], v[170:171]
	v_pk_mul_f32 v[168:169], v[94:95], v[168:169]
	v_cvt_pk_bf16_f32 v99, v170, v171
	v_cvt_pk_bf16_f32 v96, v96, v97
	s_nop 0
	v_max_f32_e32 v169, 0x554ad2e, v169
	v_max_f32_e32 v168, 0x554ad2e, v168
	v_rcp_f32_e32 v170, v168
	v_rcp_f32_e32 v171, v169
	s_nop 0
	v_pk_fma_f32 v[94:95], v[94:95], v[170:171], v[170:171] neg_lo:[1,0,0] neg_hi:[1,0,0]
	v_lshlrev_b32_e32 v170, 16, v157
	v_and_b32_e32 v171, 0xffff0000, v157
	v_pk_mul_f32 v[170:171], v[168:169], v[170:171]
	v_pk_mul_f32 v[168:169], v[92:93], v[168:169]
	v_cvt_pk_bf16_f32 v97, v170, v171
	v_cvt_pk_bf16_f32 v94, v94, v95
	v_add_u32_e32 v95, 0x4600, v133
	v_max_f32_e32 v169, 0x554ad2e, v169
	v_max_f32_e32 v168, 0x554ad2e, v168
	v_rcp_f32_e32 v170, v168
	v_rcp_f32_e32 v171, v169
	ds_write2_b32 v95, v96, v94 offset0:76 offset1:144
	ds_write2_b32 v101, v99, v97 offset0:76 offset1:144
	v_add_u32_e32 v97, 0x400, v133
	v_pk_fma_f32 v[92:93], v[92:93], v[170:171], v[170:171] neg_lo:[1,0,0] neg_hi:[1,0,0]
	v_lshlrev_b32_e32 v170, 16, v160
	v_and_b32_e32 v171, 0xffff0000, v160
	v_pk_mul_f32 v[170:171], v[168:169], v[170:171]
	v_pk_mul_f32 v[168:169], v[90:91], v[168:169]
	v_cvt_pk_bf16_f32 v95, v170, v171
	v_cvt_pk_bf16_f32 v92, v92, v93
	s_nop 0
	v_max_f32_e32 v169, 0x554ad2e, v169
	v_max_f32_e32 v168, 0x554ad2e, v168
	v_rcp_f32_e32 v170, v168
	v_rcp_f32_e32 v171, v169
	s_nop 0
	v_pk_fma_f32 v[90:91], v[90:91], v[170:171], v[170:171] neg_lo:[1,0,0] neg_hi:[1,0,0]
	v_lshlrev_b32_e32 v170, 16, v163
	v_and_b32_e32 v171, 0xffff0000, v163
	s_add_i32 s12, s17, 1
	s_cmp_ge_u32 s12, s78
	s_cbranch_scc1 .Lskip_q
	global_load_dword v122, v176, s[100:101]
	global_load_dword v124, v12, s[100:101]
	global_load_dword v129, v18, s[100:101]
	global_load_dword v150, v24, s[100:101]
	global_load_dword v153, v30, s[100:101]
	global_load_dword v157, v36, s[100:101]
	global_load_dword v160, v42, s[100:101]
	global_load_dword v163, v50, s[100:101]
.Lskip_q:
	v_cvt_pk_bf16_f32 v90, v90, v91
	v_add_u32_e32 v91, 0x4800, v133
	v_pk_mul_f32 v[168:169], v[168:169], v[170:171]
	ds_write2_b32 v91, v92, v90 offset0:84 offset1:152
	v_cvt_pk_bf16_f32 v93, v168, v169
	ds_write2_b32 v97, v95, v93 offset0:84 offset1:152
	s_cbranch_vccnz .LBB0_177
	v_add_f32_e32 v1, v166, v1
	v_add_f32_e32 v0, v167, v0
	v_add_f32_e32 v1, v1, v3
	v_add_f32_e32 v0, v0, v2
	v_add_f32_e32 v1, v1, v5
	v_add_f32_e32 v0, v0, v4
	v_add_f32_e32 v3, v1, v7
	v_add_f32_e32 v2, v0, v6
	v_max_f32_e32 v0, 0xc2e60000, v2
	v_max_f32_e32 v1, 0xc2e60000, v3
	v_sub_f32_e32 v2, v2, v167
	v_sub_f32_e32 v3, v3, v166
	v_exp_f32_e32 v0, v0
	v_exp_f32_e32 v1, v1
	v_max_f32_e32 v2, 0xc2e60000, v2
	v_max_f32_e32 v3, 0xc2e60000, v3
	v_exp_f32_e32 v2, v2
	v_exp_f32_e32 v3, v3
	ds_write_b64 v109, v[0:1]
	ds_write_b64 v110, v[2:3]
	v_max_f32_e32 v4, 0xc2e60000, v167
	v_max_f32_e32 v5, 0xc2e60000, v166
	v_exp_f32_e32 v4, v4
	v_exp_f32_e32 v5, v5
	s_nop 0
	ds_write_b64 v109, v[4:5] offset:18432
.LBB0_177:
	v_perm_b32 v0, v102, v104, s3
	v_perm_b32 v1, v98, v100, s3
	v_perm_b32 v2, v94, v96, s3
	v_perm_b32 v3, v90, v92, s3
	v_perm_b32 v4, v102, v104, s23
	v_perm_b32 v102, v127, v123, s3
	v_perm_b32 v166, v127, v123, s23
	v_perm_b32 v5, v98, v100, s23
	v_perm_b32 v103, v152, v149, s3
	v_perm_b32 v167, v152, v149, s23
	v_perm_b32 v6, v94, v96, s23
	v_perm_b32 v104, v159, v155, s3
	v_perm_b32 v168, v159, v155, s23
	v_perm_b32 v7, v90, v92, s23
	v_perm_b32 v105, v165, v162, s3
	v_perm_b32 v169, v165, v162, s23
	ds_write_b128 v134, v[0:3] offset:53248
	ds_write_b128 v134, v[4:7] offset:53392
	ds_write_b128 v134, v[102:105] offset:34816
	ds_write_b128 v134, v[166:169] offset:34960
	s_add_i32 s17, s17, 1
	s_cmp_ge_u32 s17, s78
	s_cbranch_scc1 .LBB0_172
	s_add_i32 s77, s11, 0x80
	s_add_i32 vcc_lo, s19, 0xffffff80
	s_and_b64 s[12:13], s[40:41], exec
	s_cselect_b32 s12, s77, vcc_lo
	s_add_i32 s12, s12, s18
	s_mul_hi_i32 s13, s12, 0x5000
	s_mulk_i32 s12, 0x5000
	s_add_u32 s12, s98, s12
	s_addc_u32 s13, s99, s13
	global_load_dword v123, v10, s[12:13]
	global_load_dword v127, v16, s[12:13]
	global_load_dword v149, v22, s[12:13]
	global_load_dword v152, v28, s[12:13]
	global_load_dword v155, v34, s[12:13]
	global_load_dword v159, v40, s[12:13]
	global_load_dword v162, v48, s[12:13]
	global_load_dword v165, v54, s[12:13]
	s_branch .LBB0_172
